# P0: dt-weight bf16 conversion moved from workgroups 0-31 (which also own a second adaLN item) to workgroups 224-255 when the grid is 256
# speedup vs baseline: 1.0064x; 1.0064x over previous
.LBB0_12:
	s_load_dwordx16 s[4:19], s[0:1], 0x0
	s_and_b32 s86, s2, 0xffffffc0
	s_cmp_lt_i32 s54, 1
	s_mov_b32 s94, 0
	v_mbcnt_lo_u32_b32 v194, -1, 0
	s_waitcnt lgkmcnt(0)
	v_writelane_b32 v254, s4, 16
	s_nop 1
	v_writelane_b32 v254, s5, 17
	v_writelane_b32 v254, s6, 18
	v_writelane_b32 v254, s7, 19
	v_writelane_b32 v254, s8, 20
	v_writelane_b32 v254, s9, 21
	v_writelane_b32 v254, s10, 22
	v_writelane_b32 v254, s11, 23
	v_writelane_b32 v254, s12, 24
	v_writelane_b32 v254, s13, 25
	v_writelane_b32 v254, s14, 26
	v_writelane_b32 v254, s15, 27
	v_writelane_b32 v254, s16, 28
	v_writelane_b32 v254, s17, 29
	v_writelane_b32 v254, s18, 30
	v_writelane_b32 v254, s19, 31
	s_cselect_b64 s[8:9], -1, 0
	s_cmp_gt_i32 s54, 0
	s_cselect_b64 s[2:3], -1, 0
	s_cmp_lt_i32 s55, 1
	s_cselect_b64 s[4:5], -1, 0
	s_add_u32 s84, s0, 0xf0
	s_addc_u32 s85, s1, 0
	s_or_b64 s[2:3], s[2:3], s[4:5]
	s_and_b64 vcc, exec, s[2:3]
	s_cbranch_vccnz .LBB0_28
	s_load_dword s6, s[84:85], 0x0
	v_mbcnt_hi_u32_b32 v0, -1, v194
	v_or_b32_e32 v22, s86, v0
	s_movk_i32 s2, 0x4000
	v_ashrrev_i32_e32 v23, 6, v22
	s_waitcnt lgkmcnt(0)
	s_mov_b32 s3, s93
	s_cmp_lg_u32 s6, 0x100
	s_cbranch_scc1 .Lwdt_nomap
	s_add_i32 s3, s93, 32
	s_and_b32 s3, s3, 0xff
.Lwdt_nomap:
	v_lshl_add_u32 v4, s3, 9, v22
	v_readfirstlane_b32 s12, v23
	v_cmp_gt_i32_e32 vcc, s2, v4
	s_and_saveexec_b64 s[4:5], vcc
	s_cbranch_execz .LBB0_16
	s_load_dword s2, s[84:85], 0x0
	s_load_dwordx16 s[16:31], s[0:1], 0x40
	s_add_u32 s6, s52, 0x3ce73000
	v_and_b32_e32 v0, 15, v22
	v_mov_b32_e32 v1, 0
	s_addc_u32 s7, s53, 0
	s_waitcnt lgkmcnt(0)
	s_lshl_b32 s2, s2, 9
	v_lshlrev_b32_e32 v5, 10, v0
	s_mov_b64 s[10:11], 0
	s_movk_i32 s3, 0x4840
	v_mov_b64_e32 v[2:3], s[22:23]
	v_lshlrev_b32_e32 v0, 2, v0
	s_movk_i32 s13, 0x3fff
